# P5 small-M path: 176 tiles of 16 gate+16 val columns, one K-split pass (A rows read once) and one reduction per tile; on top of v30
# speedup vs baseline: 1.0108x; 1.0081x over previous
; #define LAS __attribute__((address_space(3)))
; __device__ __forceinline__ SmallId small_id() { int tid = threadIdx.x; asm volatile("" : "+v"(tid)); SmallId i; i.w = __builtin_amdgcn_readfirstlane(tid >> 6); i.fr = tid & 15; i.fq = (tid & 63) >> 4; i.row = MP + 16 * i.w + i.fr; return i; }
; __device__ __forceinline__ void small_up(const Params& p, int l, LAS unsigned char* lds, int G, int bx) {
;     const SmallId id = small_id();
;     const bf16_t* XB = (const bf16_t*)(p.ws + WS_XB); const bf16_t* Bu = (const bf16_t*)(p.ws + WS_W + (size_t)l * W_LAYER + WO_UP); bf16_t* U = (bf16_t*)(p.ws + WS_PROJ);
;     const float* ssq = (const float*)(p.ws + WS_SSQ) + (2 * l + 1) * MPAD;
;     const float* cw = p.conv_w + (size_t)l * 3 * FF2; const float* cb = p.conv_b + (size_t)l * FF2; const float* sconv = p.state_conv + (size_t)l * 8 * 2 * FF2; float* conv_s = p.out + O_CS + (size_t)l * 8 * 2 * FF2;
;     for (int ts = G - 1 - bx; ts < FF / 32; ts += G) {
;         const int c0 = ts * 32; f32x4 acc[4];
;         const int rb0 = (c0 >> 7) * 256 + (c0 & 127);
;         { f32x4 ag[2], av[2];
;           small_mma_ksplit<4>(ag, XB, DM, Bu, DM, rb0, lds, id);
;           small_mma_ksplit<4>(av, XB, DM, Bu, DM, rb0 + 128, lds, id);
;           acc[0] = ag[0]; acc[1] = ag[1]; acc[2] = av[0]; acc[3] = av[1]; }
;         const float rs = __builtin_amdgcn_rsqf(ssq[id.row] * (1.0f / 1024.0f) + EPS);
;         const int fr = id.fr;
.LBB0_999:
	s_or_b64 exec, exec, s[0:1]
	v_readlane_b32 s8, v248, 54
	s_mul_i32 s0, s93, 0x10800
	v_readlane_b32 s14, v248, 60
	v_readlane_b32 s15, v248, 61
	s_add_u32 s40, s14, s0
	v_readlane_b32 s16, v248, 62
	s_addc_u32 s41, s15, 0
	s_mul_i32 s0, s93, 0x5800
	v_readlane_b32 s17, v248, 63
	s_add_u32 s44, s16, s0
	s_addc_u32 s45, s17, 0
	s_add_u32 s42, s40, 0x5800
	s_addc_u32 s43, s41, 0
	s_add_u32 s94, s40, 0xb000
	s_addc_u32 s95, s41, 0
	s_add_u32 s0, s52, 0x20400
	s_addc_u32 s1, s53, 0
	v_readlane_b32 s2, v247, 12
	v_writelane_b32 v246, s0, 20
	s_waitcnt lgkmcnt(0)
	v_mov_b32_e32 v0, v222
	v_readlane_b32 s3, v247, 13
	s_barrier
	v_writelane_b32 v246, s1, 21
	s_mul_i32 s96, s93, 0x16000
	s_and_b64 vcc, exec, s[2:3]
	v_readfirstlane_b32 s0, v0
	v_readlane_b32 s9, v248, 55
	v_readlane_b32 s10, v248, 56
	v_readlane_b32 s11, v248, 57
	v_readlane_b32 s12, v248, 58
	v_readlane_b32 s13, v248, 59
	v_readlane_b32 s18, v247, 0
	v_readlane_b32 s19, v247, 1
	v_readlane_b32 s20, v247, 2
	v_readlane_b32 s21, v247, 3
	v_readlane_b32 s22, v247, 4
	v_readlane_b32 s23, v247, 5
	v_readlane_b32 s2, v246, 1
	s_cmpk_lt_i32 s2, 0xb0
	s_cbranch_scc0 .LBB0_1016
	v_readlane_b32 s8, v249, 4
	s_lshl_b64 s[2:3], s[96:97], 2
	v_readlane_b32 s18, v249, 14
	v_readlane_b32 s9, v249, 5
	v_readlane_b32 s10, v249, 6
	v_readlane_b32 s11, v249, 7
	v_readlane_b32 s19, v249, 15
	s_add_u32 s8, s18, s2
	s_addc_u32 s9, s19, s3
	v_readlane_b32 s10, v246, 11
	v_readlane_b32 s11, v246, 12
	s_add_u32 s1, s10, s2
	s_addc_u32 s3, s11, s3
	s_add_u32 s2, s1, 0x83c2000
	s_addc_u32 s3, s3, 0
	s_ashr_i32 s7, s0, 6
	v_and_b32_e32 v156, 15, v0
	v_bfe_u32 v4, v0, 4, 2
	s_lshl_b32 s10, s7, 14
	v_lshlrev_b32_e32 v0, 4, v0
	s_add_i32 s10, s10, 0
	v_and_b32_e32 v0, 0x3f0, v0
	v_add_u32_e32 v157, s10, v0
	s_lshl_b32 s10, s7, 11
	s_add_i32 s10, s10, 0
	s_add_i32 s11, s10, 0x10400
	s_lshl_b32 s0, s7, 4
	v_add_u32_e32 v160, s11, v0
	s_add_i32 s11, s10, 0x14400
	s_add_i32 s0, s0, 0x8000
	v_add_u32_e32 v158, s10, v0
	v_add_u32_e32 v162, s11, v0
	s_add_i32 s11, s10, 0x18400
	s_add_i32 s10, s10, 0x1c400
	v_or_b32_e32 v2, s0, v156
	v_add_u32_e32 v164, s11, v0
	v_add_u32_e32 v166, s10, v0
	v_readlane_b32 s10, v246, 20
	s_lshl_b32 s0, s7, 7
	v_ashrrev_i32_e32 v3, 31, v2
	v_readlane_b32 s11, v246, 21
	s_lshl_b32 s7, s7, 1
	v_mov_b64_e32 v[0:1], s[8:9]
	v_lshl_add_u64 v[138:139], v[2:3], 2, s[10:11]
	v_add3_u32 v3, v156, s7, -14
	s_movk_i32 s7, 0x5800
	v_mad_i64_i32 v[140:141], s[8:9], v3, s7, v[0:1]
	s_ashr_i32 s1, s0, 31
	v_mov_b64_e32 v[0:1], s[84:85]
	s_movk_i32 s8, 0x1600
	v_mad_i64_i32 v[142:143], s[8:9], v2, s8, v[0:1]
	v_mov_b64_e32 v[0:1], s[2:3]
	s_lshl_b64 s[0:1], s[0:1], 1
	v_mad_i64_i32 v[144:145], s[2:3], v3, s7, v[0:1]
	s_add_u32 s0, s86, s0
	s_addc_u32 s1, s87, s1
	v_readlane_b32 s2, v246, 15
	s_add_u32 s2, s0, s2
	v_lshlrev_b32_e32 v96, 4, v4
	s_addc_u32 s3, s1, 0
	v_lshl_add_u64 v[146:147], s[2:3], 0, v[96:97]
	v_lshl_or_b32 v96, v156, 11, v96
	v_add_u32_e32 v159, 0x10000, v158
	v_add_u32_e32 v161, 0x14000, v158
	v_add_u32_e32 v163, 0x18000, v158
	v_add_u32_e32 v165, 0x1c000, v158
	v_lshlrev_b32_e32 v167, 2, v4
	v_cmp_lt_u32_e64 s[46:47], 13, v156
	v_cmp_gt_u32_e64 s[48:49], 14, v156
	v_cmp_eq_u32_e64 s[50:51], 15, v156
	v_lshl_add_u64 v[148:149], s[0:1], 0, v[96:97]
	v_or_b32_e32 v96, 0x80, v156
	v_readlane_b32 s2, v246, 2
	v_readlane_b32 s3, v247, 63
	v_readlane_b32 s7, v246, 1
	v_readlane_b32 s10, v246, 0
	v_readlane_b32 s12, v249, 8
	v_readlane_b32 s13, v249, 9
	v_readlane_b32 s14, v249, 10
	v_readlane_b32 s15, v249, 11
	v_readlane_b32 s16, v249, 12
	v_readlane_b32 s17, v249, 13
	v_readlane_b32 s20, v249, 16
	v_readlane_b32 s21, v249, 17
	v_readlane_b32 s22, v249, 18
	v_readlane_b32 s23, v249, 19
	s_branch .LBB0_1002

; template <int KSTEPS  >
; __device__ __forceinline__ void small_mma_ksplit(f32x4 (&acc)[2], const bf16_t* A, int lda, const bf16_t* Bt, int ldb, int n0, LAS unsigned char* lds, const SmallId& id) {
;     const int lane = id.fq * 16 + id.fr, k0 = id.w * (KSTEPS * 32);
;     f32x4 part[8][2];
; #pragma unroll
;     for (int rb = 0; rb < 8; ++rb) { part[rb][0] = (f32x4){0.f, 0.f, 0.f, 0.f}; part[rb][1] = part[rb][0]; }
;     const bf16_t* ap = A + (size_t)(MP + id.fr) * lda + k0 + 8 * id.fq;
;     const bf16_t* bp = Bt + (size_t)(n0 + id.fr) * ldb + k0 + 8 * id.fq;
; __device__ __forceinline__ void small_up(const Params& p, int l, LAS unsigned char* lds, int G, int bx) {
;     ...
;     for (int ts = G - 1 - bx; ts < FF / 32; ts += G) {
;         const int c0 = ts * 32; f32x4 acc[4];
;         const int rb0 = (c0 >> 7) * 256 + (c0 & 127);
;         { f32x4 ag[2], av[2];
;           small_mma_ksplit<4>(ag, XB, DM, Bu, DM, rb0, lds, id);
;           small_mma_ksplit<4>(av, XB, DM, Bu, DM, rb0 + 128, lds, id);
.LBB0_1002:
	s_lshr_b32 s8, s7, 3
	s_lshl_b32 s8, s8, 8
	s_lshl_b32 s9, s7, 4
	s_and_b32 s9, s9, 0x70
	s_add_i32 s32, s26, 0x40000
	v_or_b32_e32 v0, s8, v156
	v_or_b32_e32 v0, s9, v0
	v_ashrrev_i32_e32 v1, 31, v0
	v_lshlrev_b64 v[0:1], 11, v[0:1]
	v_lshl_add_u64 v[64:65], v[146:147], 0, v[0:1]
	v_mov_b32_e32 v0, 0
	s_mov_b64 s[0:1], 0
	v_mov_b32_e32 v1, v0
	v_mov_b32_e32 v2, v0
	v_mov_b32_e32 v3, v0
	v_mov_b32_e32 v4, v0
	v_mov_b32_e32 v5, v0
	v_mov_b32_e32 v6, v0
	v_mov_b32_e32 v7, v0
	v_mov_b32_e32 v8, v0
	v_mov_b32_e32 v9, v0
	v_mov_b32_e32 v10, v0
	v_mov_b32_e32 v11, v0
	v_mov_b32_e32 v12, v0
	v_mov_b32_e32 v13, v0
	v_mov_b32_e32 v14, v0
	v_mov_b32_e32 v15, v0
	v_mov_b32_e32 v16, v0
	v_mov_b32_e32 v17, v0
	v_mov_b32_e32 v18, v0
	v_mov_b32_e32 v19, v0
	v_mov_b32_e32 v20, v0
	v_mov_b32_e32 v21, v0
	v_mov_b32_e32 v22, v0
	v_mov_b32_e32 v23, v0
	v_mov_b32_e32 v24, v0
	v_mov_b32_e32 v25, v0
	v_mov_b32_e32 v26, v0
	v_mov_b32_e32 v27, v0
	v_mov_b32_e32 v36, v0
	v_mov_b32_e32 v37, v0
	v_mov_b32_e32 v38, v0
	v_mov_b32_e32 v39, v0
	v_mov_b32_e32 v28, v0
	v_mov_b32_e32 v29, v0
	v_mov_b32_e32 v30, v0
	v_mov_b32_e32 v31, v0
	v_mov_b32_e32 v32, v0
	v_mov_b32_e32 v33, v0
	v_mov_b32_e32 v34, v0
	v_mov_b32_e32 v35, v0
	v_mov_b32_e32 v40, v0
	v_mov_b32_e32 v41, v0
	v_mov_b32_e32 v42, v0
	v_mov_b32_e32 v43, v0
	v_mov_b32_e32 v44, v0
	v_mov_b32_e32 v45, v0
	v_mov_b32_e32 v46, v0
	v_mov_b32_e32 v47, v0
	v_mov_b32_e32 v48, v0
	v_mov_b32_e32 v49, v0
	v_mov_b32_e32 v50, v0
	v_mov_b32_e32 v51, v0
	v_mov_b32_e32 v52, v0
	v_mov_b32_e32 v53, v0
	v_mov_b32_e32 v54, v0
	v_mov_b32_e32 v55, v0
	v_mov_b32_e32 v56, v0
	v_mov_b32_e32 v57, v0
	v_mov_b32_e32 v58, v0
	v_mov_b32_e32 v59, v0
	v_mov_b32_e32 v60, v0
	v_mov_b32_e32 v61, v0
	v_mov_b32_e32 v62, v0
	v_mov_b32_e32 v63, v0
	s_mov_b32 s11, 0x7800000
	s_mov_b32 s12, 0x7808000
	s_mov_b32 s13, 0x7810000
	s_mov_b32 s14, 0x7818000
	s_mov_b32 s15, 0x7820000
	s_mov_b32 s16, 0x7828000
	s_mov_b32 s17, 0x7830000
; #define LAS __attribute__((address_space(3)))
; template <int KSTEPS  >
; __device__ __forceinline__ void small_mma_ksplit(f32x4 (&acc)[2], const bf16_t* A, int lda, const bf16_t* Bt, int ldb, int n0, LAS unsigned char* lds, const SmallId& id) {
;     ...
; #pragma unroll 1
;     for (int ks = 0; ks < KSTEPS; ++ks) {
;         bf16x8 a[8], b[2];
; #pragma unroll
;         for (int rb = 0; rb < 8; ++rb) a[rb] = *(const bf16x8*)(ap + (size_t)(16 * rb) * lda + 32 * ks);
;         b[0] = *(const bf16x8*)(bp + 32 * ks); b[1] = *(const bf16x8*)(bp + (size_t)16 * ldb + 32 * ks);
; #pragma unroll
;         for (int rb = 0; rb < 8; ++rb) { part[rb][0] = __builtin_amdgcn_mfma_f32_16x16x32_bf16(b[0], a[rb], part[rb][0], 0, 0, 0); part[rb][1] = __builtin_amdgcn_mfma_f32_16x16x32_bf16(b[1], a[rb], part[rb][1], 0, 0, 0); }
;     }
;     LAS f32x4* red = (LAS f32x4*)lds;
; #pragma unroll
;     for (int rb = 0; rb < 8; ++rb) { red[((id.w * 8 + rb) * 2 + 0) * 64 + lane] = part[rb][0]; red[((id.w * 8 + rb) * 2 + 1) * 64 + lane] = part[rb][1]; }
;     asm volatile("s_waitcnt lgkmcnt(0)" ::: "memory"); __syncthreads();
;     acc[0] = (f32x4){0.f, 0.f, 0.f, 0.f}; acc[1] = acc[0];
; #pragma unroll
;     for (int w2 = 0; w2 < 8; ++w2) { acc[0] += red[((w2 * 8 + id.w) * 2 + 0) * 64 + lane]; acc[1] += red[((w2 * 8 + id.w) * 2 + 1) * 64 + lane]; }
;     asm volatile("s_waitcnt lgkmcnt(0)" ::: "memory"); __syncthreads();
; __device__ __forceinline__ void small_up(const Params& p, int l, LAS unsigned char* lds, int G, int bx) {
;     ...
;           small_mma_ksplit<4>(ag, XB, DM, Bu, DM, rb0, lds, id);
;           small_mma_ksplit<4>(av, XB, DM, Bu, DM, rb0 + 128, lds, id);
;           acc[0] = ag[0]; acc[1] = ag[1]; acc[2] = av[0]; acc[3] = av[1]; }
.LBB0_1003:
	v_lshl_add_u64 v[82:83], v[148:149], 0, s[0:1]
	v_add_co_u32_e32 v70, vcc, s11, v82
	v_lshl_add_u64 v[66:67], v[64:65], 0, s[0:1]
	s_nop 1
	v_addc_co_u32_e32 v71, vcc, 0, v83, vcc
	v_add_co_u32_e32 v78, vcc, s12, v82
	s_add_u32 s0, s0, 64
	s_nop 1
	v_addc_co_u32_e32 v79, vcc, 0, v83, vcc
	v_add_co_u32_e32 v68, vcc, s26, v66
	s_addc_u32 s1, s1, 0
	s_nop 1
	v_addc_co_u32_e32 v69, vcc, 0, v67, vcc
	v_add_co_u32_e32 v74, vcc, s32, v66
	s_cmpk_lg_i32 s0, 0x100
	s_nop 1
	v_addc_co_u32_e32 v75, vcc, 0, v67, vcc
	global_load_dwordx4 v[66:69], v[68:69], off
	global_load_dwordx4 v[70:73], v[70:71], off
	global_load_dwordx4 v[74:77], v[74:75], off
	global_load_dwordx4 v[78:81], v[78:79], off
	v_add_co_u32_e32 v84, vcc, s13, v82
	s_nop 1
	v_addc_co_u32_e32 v85, vcc, 0, v83, vcc
	v_add_co_u32_e32 v86, vcc, s14, v82
	s_nop 1
	v_addc_co_u32_e32 v87, vcc, 0, v83, vcc
	global_load_dwordx4 v[180:183], v[84:85], off
	global_load_dwordx4 v[184:187], v[86:87], off
	v_add_co_u32_e32 v84, vcc, s15, v82
	s_nop 1
	v_addc_co_u32_e32 v85, vcc, 0, v83, vcc
	v_add_co_u32_e32 v86, vcc, s16, v82
	s_nop 1
	v_addc_co_u32_e32 v87, vcc, 0, v83, vcc
	global_load_dwordx4 v[188:191], v[84:85], off
	global_load_dwordx4 v[206:209], v[86:87], off
	v_add_co_u32_e32 v84, vcc, s17, v82
	s_nop 1
	v_addc_co_u32_e32 v85, vcc, 0, v83, vcc
	v_add_co_u32_e32 v82, vcc, s35, v82
	s_nop 1
	v_addc_co_u32_e32 v83, vcc, 0, v83, vcc
	global_load_dwordx4 v[210:213], v[84:85], off
	global_load_dwordx4 v[214:217], v[82:83], off
	s_waitcnt vmcnt(0) lgkmcnt(0)
	v_mfma_f32_16x16x32_bf16 v[36:39], v[66:69], v[70:73], v[36:39]
	v_mfma_f32_16x16x32_bf16 v[24:27], v[74:77], v[70:73], v[24:27]
	v_mfma_f32_16x16x32_bf16 v[20:23], v[66:69], v[78:81], v[20:23]
	v_mfma_f32_16x16x32_bf16 v[16:19], v[74:77], v[78:81], v[16:19]
	v_mfma_f32_16x16x32_bf16 v[12:15], v[66:69], v[180:183], v[12:15]
	v_mfma_f32_16x16x32_bf16 v[8:11], v[74:77], v[180:183], v[8:11]
	v_mfma_f32_16x16x32_bf16 v[4:7], v[66:69], v[184:187], v[4:7]
	v_mfma_f32_16x16x32_bf16 v[0:3], v[74:77], v[184:187], v[0:3]
	v_mfma_f32_16x16x32_bf16 v[28:31], v[66:69], v[188:191], v[28:31]
	v_mfma_f32_16x16x32_bf16 v[32:35], v[74:77], v[188:191], v[32:35]
	v_mfma_f32_16x16x32_bf16 v[40:43], v[66:69], v[206:209], v[40:43]
	v_mfma_f32_16x16x32_bf16 v[44:47], v[74:77], v[206:209], v[44:47]
	v_mfma_f32_16x16x32_bf16 v[48:51], v[66:69], v[210:213], v[48:51]
	v_mfma_f32_16x16x32_bf16 v[52:55], v[74:77], v[210:213], v[52:55]
	v_mfma_f32_16x16x32_bf16 v[56:59], v[66:69], v[214:217], v[56:59]
	v_mfma_f32_16x16x32_bf16 v[60:63], v[74:77], v[214:217], v[60:63]
	s_cbranch_scc1 .LBB0_1003
	s_add_i32 s9, s9, s8
	v_add_u32_e32 v64, s9, v96
	v_ashrrev_i32_e32 v65, 31, v64
	v_lshlrev_b64 v[64:65], 11, v[64:65]
	ds_write_b128 v157, v[36:39]
	ds_write_b128 v157, v[24:27] offset:1024
	ds_write_b128 v157, v[20:23] offset:2048
	ds_write_b128 v157, v[16:19] offset:3072
	ds_write_b128 v157, v[12:15] offset:4096
	ds_write_b128 v157, v[8:11] offset:5120
	ds_write_b128 v157, v[4:7] offset:6144
	ds_write_b128 v157, v[0:3] offset:7168
	ds_write_b128 v157, v[28:31] offset:8192
	ds_write_b128 v157, v[32:35] offset:9216
	ds_write_b128 v157, v[40:43] offset:10240
	ds_write_b128 v157, v[44:47] offset:11264
	ds_write_b128 v157, v[48:51] offset:12288
	ds_write_b128 v157, v[52:55] offset:13312
	ds_write_b128 v157, v[56:59] offset:14336
	ds_write_b128 v157, v[60:63] offset:15360
	v_lshl_add_u64 v[130:131], v[146:147], 0, v[64:65]
	s_waitcnt lgkmcnt(0)
	s_waitcnt lgkmcnt(0)
	s_barrier
	ds_read_b128 v[92:95], v158
	ds_read_b128 v[28:31], v158 offset:1024
	ds_read_b128 v[88:91], v158 offset:16384
	ds_read_b128 v[24:27], v158 offset:17408
	ds_read_b128 v[84:87], v158 offset:32768
	ds_read_b128 v[20:23], v158 offset:33792
	ds_read_b128 v[80:83], v158 offset:49152
	ds_read_b128 v[16:19], v158 offset:50176
	ds_read_b128 v[76:79], v159
	ds_read_b128 v[12:15], v160
	ds_read_b128 v[72:75], v161
	ds_read_b128 v[8:11], v162
	ds_read_b128 v[68:71], v163
	ds_read_b128 v[4:7], v164
	ds_read_b128 v[64:67], v165
	ds_read_b128 v[0:3], v166
	s_waitcnt lgkmcnt(0)
	v_mov_b32_e32 v32, 0
	s_mov_b64 s[0:1], 0
	v_mov_b32_e32 v33, v32
	v_mov_b32_e32 v34, v32
	v_mov_b32_e32 v35, v32
	v_mov_b32_e32 v36, v32
	v_mov_b32_e32 v37, v32
	v_mov_b32_e32 v38, v32
	v_mov_b32_e32 v39, v32
	v_mov_b32_e32 v40, v32
	v_mov_b32_e32 v41, v32
	v_mov_b32_e32 v42, v32
	v_mov_b32_e32 v43, v32
	v_mov_b32_e32 v44, v32
	v_mov_b32_e32 v45, v32
	v_mov_b32_e32 v46, v32
	v_mov_b32_e32 v47, v32
	v_mov_b32_e32 v48, v32
	v_mov_b32_e32 v49, v32
	v_mov_b32_e32 v50, v32
	v_mov_b32_e32 v51, v32
	v_mov_b32_e32 v52, v32
	v_mov_b32_e32 v53, v32
	v_mov_b32_e32 v54, v32
	v_mov_b32_e32 v55, v32
	v_mov_b32_e32 v56, v32
	v_mov_b32_e32 v57, v32
	v_mov_b32_e32 v58, v32
	v_mov_b32_e32 v59, v32
	v_mov_b32_e32 v102, v32
	v_mov_b32_e32 v103, v32
	v_mov_b32_e32 v104, v32
	v_mov_b32_e32 v105, v32
	v_mov_b32_e32 v60, v32
	v_mov_b32_e32 v61, v32
	v_mov_b32_e32 v62, v32
	v_mov_b32_e32 v63, v32
	v_mov_b32_e32 v98, v32
	v_mov_b32_e32 v99, v32
	v_mov_b32_e32 v100, v32
	v_mov_b32_e32 v101, v32
	v_mov_b32_e32 v106, v32
	v_mov_b32_e32 v107, v32
	v_mov_b32_e32 v108, v32
	v_mov_b32_e32 v109, v32
	v_mov_b32_e32 v110, v32
	v_mov_b32_e32 v111, v32
	v_mov_b32_e32 v112, v32
	v_mov_b32_e32 v113, v32
	v_mov_b32_e32 v114, v32
	v_mov_b32_e32 v115, v32
	v_mov_b32_e32 v116, v32
	v_mov_b32_e32 v117, v32
	v_mov_b32_e32 v118, v32
	v_mov_b32_e32 v119, v32
	v_mov_b32_e32 v120, v32
	v_mov_b32_e32 v121, v32
	v_mov_b32_e32 v122, v32
	v_mov_b32_e32 v123, v32
	v_mov_b32_e32 v124, v32
	v_mov_b32_e32 v125, v32
	v_mov_b32_e32 v126, v32
	v_mov_b32_e32 v127, v32
	v_mov_b32_e32 v128, v32
	v_mov_b32_e32 v129, v32
	s_waitcnt lgkmcnt(0)
	s_barrier
	v_mov_b64_e32 v[106:107], v[28:29]
	v_mov_b64_e32 v[108:109], v[30:31]
	v_mov_b64_e32 v[110:111], v[24:25]
	v_mov_b64_e32 v[112:113], v[26:27]
	v_mov_b64_e32 v[114:115], v[20:21]
	v_mov_b64_e32 v[116:117], v[22:23]
	v_mov_b64_e32 v[118:119], v[16:17]
	v_mov_b64_e32 v[120:121], v[18:19]
	v_mov_b64_e32 v[122:123], v[12:13]
	v_mov_b64_e32 v[124:125], v[14:15]
	v_mov_b64_e32 v[126:127], v[8:9]
	v_mov_b64_e32 v[128:129], v[10:11]
	v_mov_b64_e32 v[130:131], v[4:5]
	v_mov_b64_e32 v[132:133], v[6:7]
	v_mov_b64_e32 v[134:135], v[0:1]
	v_mov_b64_e32 v[136:137], v[2:3]
	s_branch .Lmy_up_epi

; __device__ __forceinline__ void small_up(const Params& p, int l, LAS unsigned char* lds, int G, int bx) {
;     ...
;         const float rs = __builtin_amdgcn_rsqf(ssq[id.row] * (1.0f / 1024.0f) + EPS);
;         const int fr = id.fr;
; #pragma unroll
;         for (int nb = 0; nb < 2; ++nb) {
;             const int colg = c0 + 16 * nb + 4 * id.fq, colv = FF + colg;
;             const f32x4 cg_ = acc[nb] * rs, cv_ = acc[2 + nb] * rs;
;             f32x4 hg = (f32x4){0.f, 0.f, 0.f, 0.f}, hv = hg;
;             if (fr >= 14) { const float* sp = sconv + (size_t)(id.w * 2 + (fr - 14)) * FF2; hg = *(const f32x4*)(sp + colg); hv = *(const f32x4*)(sp + colv); }
;             const f32x4 w0g = *(const f32x4*)(cw + colg), w1g = *(const f32x4*)(cw + FF2 + colg), w2g = *(const f32x4*)(cw + 2 * FF2 + colg), bg = *(const f32x4*)(cb + colg);
.Lmy_up_epi:
	global_load_dword v168, v[138:139], off
	v_lshl_or_b32 v150, s7, 4, v167
	v_add_u32_e32 v154, 0xb00, v150
	v_ashrrev_i32_e32 v155, 31, v154
	s_and_saveexec_b64 s[0:1], s[48:49]
	s_xor_b64 s[0:1], exec, s[0:1]
	s_or_saveexec_b64 s[0:1], s[0:1]
	v_ashrrev_i32_e32 v151, 31, v150
	v_mov_b32_e32 v98, 0
	v_lshl_add_u64 v[152:153], v[150:151], 2, v[140:141]
	v_mov_b32_e32 v99, 0
	v_mov_b32_e32 v100, 0
	v_mov_b32_e32 v101, 0
	v_mov_b32_e32 v102, 0
	v_mov_b32_e32 v103, 0
	v_mov_b32_e32 v104, 0
	v_mov_b32_e32 v105, 0
	s_xor_b64 exec, exec, s[0:1]
	s_cbranch_execz .LBB0_1008
	v_add_co_u32_e32 v98, vcc, 0x2000, v152
	s_nop 1
	v_addc_co_u32_e32 v99, vcc, 0, v153, vcc
	global_load_dwordx4 v[102:105], v[152:153], off
	s_nop 0
	global_load_dwordx4 v[98:101], v[98:99], off offset:3072

; __device__ __forceinline__ unsigned cvt_pk_bf16(float lo, float hi) { unsigned r; asm volatile("v_cvt_pk_bf16_f32 %0, %1, %2" : "=v"(r) : "v"(lo), "v"(hi)); return r; }
; __device__ __forceinline__ float ror1(float x) { return __builtin_bit_cast(float, __builtin_amdgcn_update_dpp(0, __builtin_bit_cast(int, x), 0x121, 0xf, 0xf, false)); }
; __device__ __forceinline__ float ror2(float x) { return __builtin_bit_cast(float, __builtin_amdgcn_update_dpp(0, __builtin_bit_cast(int, x), 0x122, 0xf, 0xf, false)); }
; __device__ __forceinline__ void small_up(const Params& p, int l, LAS unsigned char* lds, int G, int bx) {
;     ...
;         for (int nb = 0; nb < 2; ++nb) {
;             const int colg = c0 + 16 * nb + 4 * id.fq, colv = FF + colg;
;             const f32x4 cg_ = acc[nb] * rs, cv_ = acc[2 + nb] * rs;
;             f32x4 hg = (f32x4){0.f, 0.f, 0.f, 0.f}, hv = hg;
;             if (fr >= 14) { const float* sp = sconv + (size_t)(id.w * 2 + (fr - 14)) * FF2; hg = *(const f32x4*)(sp + colg); hv = *(const f32x4*)(sp + colv); }
;             const f32x4 w0g = *(const f32x4*)(cw + colg), w1g = *(const f32x4*)(cw + FF2 + colg), w2g = *(const f32x4*)(cw + 2 * FF2 + colg), bg = *(const f32x4*)(cb + colg);
;             const f32x4 w0v = *(const f32x4*)(cw + colv), w1v = *(const f32x4*)(cw + FF2 + colv), w2v = *(const f32x4*)(cw + 2 * FF2 + colv), bv = *(const f32x4*)(cb + colv);
;             f32x4 p1g, p2g, p1v, p2v;
; #pragma unroll
;             for (int j = 0; j < 4; ++j) {
;                 p1g[j] = ror1(fr == 15 ? hg[j] : cg_[j]); p2g[j] = ror2(fr >= 14 ? hg[j] : cg_[j]);
;                 p1v[j] = ror1(fr == 15 ? hv[j] : cv_[j]); p2v[j] = ror2(fr >= 14 ? hv[j] : cv_[j]);
;             }
;             const f32x4 hcg = bg + w0g * p2g + w1g * p1g + w2g * cg_;
;             const f32x4 hcv = bv + w0v * p2v + w1v * p1v + w2v * cv_;
;             const f32x2 ga = gelu_pk((f32x2){hcg[0], hcg[1]}), gb2 = gelu_pk((f32x2){hcg[2], hcg[3]});
;             u32x2 w; w.x = cvt_pk_bf16(ga.x * hcv[0], ga.y * hcv[1]); w.y = cvt_pk_bf16(gb2.x * hcv[2], gb2.y * hcv[3]);
;             *(u32x2*)(U + (size_t)id.row * FF + colg) = w;
;             if (fr >= 14) { float* cp = conv_s + (size_t)(id.w * 2 + (fr - 14)) * FF2; *(f32x4*)(cp + colg) = cg_; *(f32x4*)(cp + colv) = cv_; }
;         }
.LBB0_1010:
	s_or_b64 exec, exec, s[0:1]
	s_branch .LBB0_1001
	v_add_u32_e32 v82, 0xb10, v150
	v_ashrrev_i32_e32 v83, 31, v82
	s_and_saveexec_b64 s[0:1], s[48:49]
	s_xor_b64 s[0:1], exec, s[0:1]
	s_or_saveexec_b64 s[0:1], s[0:1]
	v_mov_b32_e32 v64, 0
	v_mov_b32_e32 v65, 0
	v_mov_b32_e32 v66, 0
	v_mov_b32_e32 v67, 0
	v_mov_b32_e32 v68, 0
	v_mov_b32_e32 v69, 0
	v_mov_b32_e32 v70, 0
	v_mov_b32_e32 v71, 0
	s_xor_b64 exec, exec, s[0:1]
	s_cbranch_execz .LBB0_1014
	v_add_co_u32_e32 v64, vcc, 0x2000, v152
	s_nop 1
	v_addc_co_u32_e32 v65, vcc, 0, v153, vcc
	global_load_dwordx4 v[68:71], v[152:153], off offset:64
	s_nop 0
	global_load_dwordx4 v[64:67], v[64:65], off offset:3136
